# attention epilogue: 8 dwordx2 row stores -> 4 dwordx4 via v_permlane32_swap pairs
# baseline (speedup 1.0000x reference)
; __device__ __forceinline__ unsigned pk2(float lo, float hi) { unsigned r; asm("v_cvt_pk_bf16_f32 %0, %1, %2" : "=v"(r) : "v"(lo), "v"(hi)); return r; }
; __device__ __forceinline__ void attn_block(KP p, LAS unsigned char* lds, int bh, int q0) {
;     ...
;     const int b = bh >> 2, hd = bh & 3; const size_t grow = (size_t)b * SEQ + qrow;
;     if (lh == 0) ((float*)(ws + OFF_SSQM))[grow * 4 + hd] = ss;
;     bf16_t* od = (bf16_t*)(ws + OFF_MIX) + grow * DM + 256 + 64 * hd + 4 * lh;
; #pragma unroll
;     for (int g = 0; g < 4; ++g) {
;         u32x2 a, c; a.x = pk2(o0[4 * g], o0[4 * g + 1]); a.y = pk2(o0[4 * g + 2], o0[4 * g + 3]); c.x = pk2(o1[4 * g], o1[4 * g + 1]); c.y = pk2(o1[4 * g + 2], o1[4 * g + 3]);
;         *(u32x2*)(od + 8 * g) = a; *(u32x2*)(od + 32 + 8 * g) = c;
;     }
;     __syncthreads();
.LBB0_240:
	s_or_b64 exec, exec, s[6:7]
	v_lshlrev_b64 v[34:35], 11, v[34:35]
	v_lshl_add_u64 v[34:35], s[94:95], 0, v[34:35]
	s_lshl_b32 s18, s8, 1
	v_lshl_add_u64 v[34:35], v[34:35], 0, s[18:19]
	v_lshlrev_b32_e32 v0, 1, v145
	v_lshl_add_u64 v[34:35], v[34:35], 0, v[0:1]
	v_cvt_pk_bf16_f32 v2, v2, v3
	v_cvt_pk_bf16_f32 v3, v4, v5
	v_cvt_pk_bf16_f32 v4, v6, v7
	v_cvt_pk_bf16_f32 v5, v8, v9
	v_cvt_pk_bf16_f32 v18, v18, v19
	v_cvt_pk_bf16_f32 v19, v20, v21
	v_cvt_pk_bf16_f32 v20, v22, v23
	v_cvt_pk_bf16_f32 v21, v24, v25
	s_mov_b64 s[6:7], 0x110b0200
	s_waitcnt lgkmcnt(0)
	v_lshl_add_u64 v[36:37], v[34:35], 0, s[6:7]
	v_and_b32_e32 v0, 32, v193
	v_lshrrev_b32_e32 v0, 2, v0
	v_add_u32_e32 v36, v0, v36
	v_permlane32_swap_b32_e32 v18, v20
	v_permlane32_swap_b32_e32 v19, v21
	global_store_dwordx4 v[36:37], v[18:21], off
	v_permlane32_swap_b32_e32 v2, v4
	v_permlane32_swap_b32_e32 v3, v5
	global_store_dwordx4 v[36:37], v[2:5], off offset:64
	v_cvt_pk_bf16_f32 v26, v26, v27
	v_cvt_pk_bf16_f32 v27, v28, v29
	v_cvt_pk_bf16_f32 v28, v30, v31
	v_cvt_pk_bf16_f32 v29, v32, v33
	v_cvt_pk_bf16_f32 v10, v10, v11
	v_cvt_pk_bf16_f32 v11, v12, v13
	v_cvt_pk_bf16_f32 v12, v14, v15
	v_cvt_pk_bf16_f32 v13, v16, v17
	s_add_i32 s54, s54, s52
	s_cmpk_gt_i32 s54, 0xff
	s_nop 1
	v_permlane32_swap_b32_e32 v26, v28
	v_permlane32_swap_b32_e32 v27, v29
	global_store_dwordx4 v[36:37], v[26:29], off offset:32
	v_permlane32_swap_b32_e32 v10, v12
	v_permlane32_swap_b32_e32 v11, v13
	global_store_dwordx4 v[36:37], v[10:13], off offset:96
	s_barrier
	s_cbranch_scc1 .LBB0_277

; #define LAS __attribute__((address_space(3)))
; __device__ __forceinline__ unsigned pk2(float lo, float hi) { unsigned r; asm("v_cvt_pk_bf16_f32 %0, %1, %2" : "=v"(r) : "v"(lo), "v"(hi)); return r; }
; __device__ __forceinline__ void attn_block(KP p, LAS unsigned char* lds, int bh, int q0) {
;     int tid = threadIdx.x; asm volatile("" : "+v"(tid));
;     const int lane = tid & 63, w = __builtin_amdgcn_readfirstlane(tid >> 6), lr = lane & 31, lh = lane >> 5;
;     unsigned char* ws = p->ws;
;     const bf16_t* Qg = (const bf16_t*)(ws + OFF_Q) + (size_t)bh * SEQ * 96;
;     const bf16_t* Kg = (const bf16_t*)(ws + OFF_K) + (size_t)bh * SEQ * 96;
;     const bf16_t* Vg = (const bf16_t*)(ws + OFF_VT) + (size_t)bh * 64 * SEQ;
;     const int qrow = q0 + 32 * w + lr, wave_q0 = q0 + 32 * w;
;     bf16x8 qf[6];
; #pragma unroll
;     for (int ks = 0; ks < 6; ++ks) qf[ks] = *(const bf16x8*)(Qg + (size_t)qrow * 96 + 16 * ks + 8 * lh);
;     f32x16 o0, o1;
; #pragma unroll
;     for (int i = 0; i < 16; ++i) { o0[i] = 0.f; o1[i] = 0.f; }
;     float mrun = -1e30f, lrun = 0.f;
;     const int nst = (q0 + 256) / 128;
;     u32x4 rk[3], rv[2];
; #pragma unroll
;     for (int i = 0; i < 3; ++i) { const int q = tid + 512 * i; rk[i] = *(const u32x4*)(Kg + (size_t)(q / 12) * 96 + 8 * (q % 12)); }
; #pragma unroll
;     for (int i = 0; i < 2; ++i) { const int q = tid + 512 * i; rv[i] = *(const u32x4*)(Vg + (size_t)(q >> 4) * SEQ + 8 * (q & 15)); }
;     ...
;     const int b = bh >> 2, hd = bh & 3; const size_t grow = (size_t)b * SEQ + qrow;
;     if (lh == 0) ((float*)(ws + OFF_SSQM))[grow * 4 + hd] = ss;
;     bf16_t* od = (bf16_t*)(ws + OFF_MIX) + grow * DM + 256 + 64 * hd + 4 * lh;
; #pragma unroll
;     for (int g = 0; g < 4; ++g) {
;         u32x2 a, c; a.x = pk2(o0[4 * g], o0[4 * g + 1]); a.y = pk2(o0[4 * g + 2], o0[4 * g + 3]); c.x = pk2(o1[4 * g], o1[4 * g + 1]); c.y = pk2(o1[4 * g + 2], o1[4 * g + 3]);
;         *(u32x2*)(od + 8 * g) = a; *(u32x2*)(od + 32 + 8 * g) = c;
;     }
;     __syncthreads();
.LBB0_259:
	s_or_b64 exec, exec, s[6:7]
	v_lshlrev_b64 v[34:35], 11, v[34:35]
	v_lshl_add_u64 v[34:35], s[94:95], 0, v[34:35]
	s_lshl_b32 s18, s83, 7
	v_lshl_add_u64 v[34:35], v[34:35], 0, s[18:19]
	v_lshlrev_b32_e32 v0, 1, v145
	v_lshl_add_u64 v[34:35], v[34:35], 0, v[0:1]
	v_cvt_pk_bf16_f32 v2, v2, v3
	v_cvt_pk_bf16_f32 v3, v4, v5
	v_cvt_pk_bf16_f32 v4, v6, v7
	v_cvt_pk_bf16_f32 v5, v8, v9
	v_cvt_pk_bf16_f32 v18, v18, v19
	v_cvt_pk_bf16_f32 v19, v20, v21
	v_cvt_pk_bf16_f32 v20, v22, v23
	v_cvt_pk_bf16_f32 v21, v24, v25
	s_mov_b64 s[6:7], 0x110b0200
	s_waitcnt lgkmcnt(0)
	v_lshl_add_u64 v[36:37], v[34:35], 0, s[6:7]
	v_and_b32_e32 v0, 32, v193
	v_lshrrev_b32_e32 v0, 2, v0
	v_add_u32_e32 v36, v0, v36
	v_permlane32_swap_b32_e32 v18, v20
	v_permlane32_swap_b32_e32 v19, v21
	global_store_dwordx4 v[36:37], v[18:21], off
	v_permlane32_swap_b32_e32 v2, v4
	v_permlane32_swap_b32_e32 v3, v5
	global_store_dwordx4 v[36:37], v[2:5], off offset:64
	v_cvt_pk_bf16_f32 v26, v26, v27
	v_cvt_pk_bf16_f32 v27, v28, v29
	v_cvt_pk_bf16_f32 v28, v30, v31
	v_cvt_pk_bf16_f32 v29, v32, v33
	v_cvt_pk_bf16_f32 v10, v10, v11
	v_cvt_pk_bf16_f32 v11, v12, v13
	v_cvt_pk_bf16_f32 v12, v14, v15
	v_cvt_pk_bf16_f32 v13, v16, v17
	v_mov_b32_e32 v22, v167
	s_nop 1
	v_permlane32_swap_b32_e32 v26, v28
	v_permlane32_swap_b32_e32 v27, v29
	global_store_dwordx4 v[36:37], v[26:29], off offset:32
	v_permlane32_swap_b32_e32 v10, v12
	v_permlane32_swap_b32_e32 v11, v13
	global_store_dwordx4 v[36:37], v[10:13], off offset:96
	s_barrier
	s_xor_b32 s18, s55, 0xf00
	v_readfirstlane_b32 s6, v22
	s_ashr_i32 s6, s6, 1
	s_andn2_b32 s6, s6, 31
	v_and_b32_e32 v23, 31, v22
	s_add_i32 s6, s6, s18
	v_bfe_u32 v157, v22, 5, 1
	v_or_b32_e32 v142, s6, v23
	v_mov_b64_e32 v[2:3], s[10:11]
	v_mad_i64_i32 v[2:3], s[10:11], v142, s57, v[2:3]
	v_lshlrev_b32_e32 v144, 4, v157
	v_mov_b32_e32 v145, v1
	v_lshl_add_u64 v[2:3], v[2:3], 0, v[144:145]
	v_mul_hi_i32 v0, v22, s63
	global_load_dwordx4 v[66:69], v[2:3], off
	global_load_dwordx4 v[70:73], v[2:3], off offset:32
	global_load_dwordx4 v[74:77], v[2:3], off offset:64
	global_load_dwordx4 v[78:81], v[2:3], off offset:96
	global_load_dwordx4 v[82:85], v[2:3], off offset:128
	global_load_dwordx4 v[86:89], v[2:3], off offset:160
	v_lshrrev_b32_e32 v2, 31, v0
	v_ashrrev_i32_e32 v0, 1, v0
	v_add_u32_e32 v24, v0, v2
	v_mul_lo_u32 v0, v24, 12
	v_add_u32_e32 v14, 0x200, v22
	v_sub_u32_e32 v25, v22, v0
	v_mul_hi_i32 v0, v14, s63
	v_lshrrev_b32_e32 v4, 31, v0
	v_ashrrev_i32_e32 v0, 1, v0
	v_add_u32_e32 v26, v0, v4
	v_mul_lo_u32 v0, v26, 12
	v_sub_u32_e32 v27, v14, v0
	v_add_u32_e32 v0, 0x400, v22
	v_mul_hi_i32 v6, v0, s63
	v_lshrrev_b32_e32 v7, 31, v6
	v_ashrrev_i32_e32 v6, 1, v6
	v_add_u32_e32 v28, v6, v7
	v_mul_lo_u32 v6, v28, 12
	v_sub_u32_e32 v29, v0, v6
	v_lshlrev_b32_e32 v0, 3, v22
	v_and_b32_e32 v158, 0x78, v0
	v_ashrrev_i32_e32 v10, 4, v22
	v_ashrrev_i32_e32 v14, 4, v14
	v_lshlrev_b32_e32 v0, 1, v158
	v_ashrrev_i32_e32 v11, 31, v10
	v_ashrrev_i32_e32 v15, 31, v14
	v_lshl_add_u64 v[8:9], s[12:13], 0, v[0:1]
	v_lshlrev_b64 v[12:13], 13, v[10:11]
	v_lshlrev_b64 v[16:17], 13, v[14:15]
	v_lshlrev_b32_e32 v2, 3, v25
	v_lshlrev_b32_e32 v6, 3, v29
	v_lshl_add_u64 v[18:19], v[8:9], 0, v[16:17]
	v_lshl_add_u64 v[8:9], v[8:9], 0, v[12:13]
	v_ashrrev_i32_e32 v3, 31, v2
	v_lshlrev_b32_e32 v4, 3, v27
	v_ashrrev_i32_e32 v7, 31, v6
	global_load_dwordx4 v[94:97], v[18:19], off
	global_load_dwordx4 v[90:93], v[8:9], off
	v_mov_b64_e32 v[8:9], s[8:9]
	v_ashrrev_i32_e32 v5, 31, v4
	v_mad_i64_i32 v[18:19], s[8:9], v28, s57, v[8:9]
	v_lshlrev_b64 v[6:7], 1, v[6:7]
	v_mad_i64_i32 v[20:21], s[8:9], v26, s57, v[8:9]
	v_mad_i64_i32 v[8:9], s[8:9], v24, s57, v[8:9]
	v_lshlrev_b64 v[2:3], 1, v[2:3]
	v_lshl_add_u64 v[18:19], v[18:19], 0, v[6:7]
	v_lshlrev_b64 v[4:5], 1, v[4:5]
	v_lshl_add_u64 v[8:9], v[8:9], 0, v[2:3]
	v_lshl_add_u64 v[20:21], v[20:21], 0, v[4:5]
	global_load_dwordx4 v[102:105], v[18:19], off
	global_load_dwordx4 v[98:101], v[20:21], off
	global_load_dwordx4 v[106:109], v[8:9], off
	v_and_b32_e32 v0, 15, v22
	v_lshl_add_u64 v[8:9], s[24:25], 0, v[16:17]
	v_lshlrev_b32_e32 v0, 4, v0
	v_lshl_add_u64 v[146:147], v[8:9], 0, v[0:1]
	v_lshl_add_u64 v[8:9], s[24:25], 0, v[12:13]
	v_lshl_add_u64 v[148:149], v[8:9], 0, v[0:1]
	v_mov_b64_e32 v[8:9], s[36:37]
	v_mul_lo_u32 v173, v10, s64
	v_mad_i64_i32 v[10:11], s[12:13], v28, s57, v[8:9]
	v_lshl_add_u64 v[150:151], v[10:11], 0, v[6:7]
	v_mad_i64_i32 v[6:7], s[12:13], v26, s57, v[8:9]
	v_mul_lo_u32 v174, v14, s64
	v_lshl_add_u64 v[152:153], v[6:7], 0, v[4:5]
	v_mad_i64_i32 v[4:5], s[12:13], v24, s57, v[8:9]
	v_mov_b32_e32 v14, v1
	v_mov_b32_e32 v15, v1
	v_mul_u32_u24_e32 v160, 0xd0, v23
	v_mul_u32_u24_e32 v161, 0x110, v23
	v_mul_lo_u32 v166, v24, s58
	v_lshlrev_b32_e32 v168, 4, v25
	v_mul_lo_u32 v169, v26, s58
	v_lshlrev_b32_e32 v170, 4, v27
	v_mul_lo_u32 v171, v28, s58
	v_lshlrev_b32_e32 v172, 4, v29
	v_lshl_add_u64 v[154:155], v[4:5], 0, v[2:3]
	v_mov_b32_e32 v0, v1
	v_mov_b32_e32 v2, v1
	v_mov_b32_e32 v3, v1
	v_mov_b32_e32 v4, v1
	v_mov_b32_e32 v5, v1
	v_mov_b32_e32 v6, v1
	v_mov_b32_e32 v7, v1
	v_mov_b32_e32 v8, v1
	v_mov_b32_e32 v9, v1
	v_mov_b32_e32 v10, v1
	v_mov_b32_e32 v11, v1
	v_mov_b32_e32 v12, v1
	v_mov_b32_e32 v13, v1
	v_mov_b64_e32 v[32:33], v[14:15]
	s_addk_i32 s18, 0x100
	v_mov_b64_e32 v[30:31], v[12:13]
	v_mov_b64_e32 v[28:29], v[10:11]
	v_mov_b64_e32 v[26:27], v[8:9]
	v_mov_b64_e32 v[24:25], v[6:7]
	v_mov_b64_e32 v[22:23], v[4:5]
	v_mov_b64_e32 v[20:21], v[2:3]
	v_mov_b64_e32 v[18:19], v[0:1]
	v_mov_b64_e32 v[16:17], v[14:15]
	s_lshl_b32 s8, s83, 6
	s_mov_b32 s7, 0
	v_ashrrev_i32_e32 v143, 31, v142
	v_lshlrev_b32_e32 v159, 3, v157
	s_lshr_b32 s9, s18, 7
	s_or_b32 s10, s6, 31
	v_lshlrev_b32_e32 v145, 2, v157
	v_mov_b32_e32 v175, 0
	v_mov_b32_e32 v176, 0xf149f2ca
	s_mov_b32 s11, 63
	v_mov_b64_e32 v[14:15], v[12:13]
	v_mov_b64_e32 v[12:13], v[10:11]
	v_mov_b64_e32 v[10:11], v[8:9]
	v_mov_b64_e32 v[8:9], v[6:7]
	v_mov_b64_e32 v[6:7], v[4:5]
	v_mov_b64_e32 v[4:5], v[2:3]
	v_mov_b64_e32 v[2:3], v[0:1]
	s_branch .LBB0_262
